# v10: + gla gates log-sigmoid dead range guards removed (G1+G3), NA trims
# speedup vs baseline: 1.0007x; 1.0007x over previous
; #define LAS __attribute__((address_space(3)))
; __device__ __forceinline__ unsigned pk_bf16(float lo, float hi) { unsigned r; asm volatile("v_cvt_pk_bf16_f32 %0, %1, %2" : "=v"(r) : "v"(lo), "v"(hi)); return r; }
; __device__ __forceinline__ f32x4 mfma16(bf16x8 a, bf16x8 b, f32x4 c) { return __builtin_amdgcn_mfma_f32_16x16x32_bf16(a, b, c, 0, 0, 0); }
; __device__ __forceinline__ void gla_prep(const PrepRegs& R, LAS unsigned char* lds, int wave, int fr, int fq) {
;     ...
;     for (int q = 0; q < 3; ++q) { const int tile = wave * 3 + q, mi = tile / 6, ni = tile % 6, dir = ni / 3, c = (ni % 3) * 16 + fr;
;         const f32x4 acc = mfma16(as_bf8(R.ga[q]), as_bf8(R.bw[q]), (f32x4){0.f, 0.f, 0.f, 0.f});
;         float g[4];
; #pragma unroll
;         for (int i = 0; i < 4; ++i) { const float sv = acc[i] + R.bias[q]; g[i] = (fminf(sv, 0.f) - __logf(1.f + __expf(-fabsf(sv)))) * (1.0f / 16.0f); }
;         u32x2 w2; w2.x = pk_bf16(g[0], g[1]); w2.y = pk_bf16(g[2], g[3]);
;         *(LAS u32x2*)(lds + GL_GT + (dir * 48 + c) * 144 + (mi * 16 + fq * 4) * 2) = w2; }
.LBB0_698:
	s_or_b64 exec, exec, s[4:5]
	s_waitcnt vmcnt(1)
	v_cvt_pk_bf16_f32 v30, v113, v112
	v_cvt_pk_bf16_f32 v31, v115, v114
	v_cvt_pk_bf16_f32 v32, v117, v116
	v_cvt_pk_bf16_f32 v33, v119, v118
	v_and_b32_e32 v30, v140, v30
	v_and_b32_e32 v31, v140, v31
	v_and_b32_e32 v32, v140, v32
	v_and_b32_e32 v33, v140, v33
	v_cvt_pk_bf16_f32 v34, v121, v120
	v_cvt_pk_bf16_f32 v35, v123, v122
	v_cvt_pk_bf16_f32 v36, v125, v124
	v_cvt_pk_bf16_f32 v37, v127, v126
	v_and_b32_e32 v34, v141, v34
	v_and_b32_e32 v35, v141, v35
	v_and_b32_e32 v36, v141, v36
	v_and_b32_e32 v37, v141, v37
	v_cvt_pk_bf16_f32 v38, v133, v132
	v_cvt_pk_bf16_f32 v39, v135, v134
	v_cvt_pk_bf16_f32 v40, v137, v136
	v_cvt_pk_bf16_f32 v41, v139, v138
	v_and_b32_e32 v38, v142, v38
	v_and_b32_e32 v39, v142, v39
	v_and_b32_e32 v40, v142, v40
	v_and_b32_e32 v41, v142, v41
	v_mfma_f32_16x16x32_bf16 v[18:21], v[18:21], v[30:33], 0
	s_barrier
	v_or_b32_e32 v33, 2, v61
	v_or_b32_e32 v47, 34, v61
	s_waitcnt vmcnt(4)
	s_nop 3
	v_add_f32_e32 v18, v78, v18
	v_mul_f32_e64 v30, |v18|, s33
	v_exp_f32_e32 v30, v30
	v_add_f32_e32 v19, v78, v19
	v_min_f32_e32 v18, 0, v18
	v_add_f32_e32 v20, v78, v20
	v_add_f32_e32 v30, 1.0, v30
	v_add_f32_e32 v21, v78, v21
	v_or_b32_e32 v58, 37, v61
	v_log_f32_e32 v30, v30
	v_mul_f32_e64 v31, |v19|, s33
	v_exp_f32_e32 v31, v31
	v_min_f32_e32 v19, 0, v19
	v_mul_f32_e32 v32, 0x3f317217, v30
	v_fma_f32 v32, v30, s2, -v32
	v_fmac_f32_e32 v32, 0x3377d1cf, v30
	v_fmac_f32_e32 v32, 0x3f317217, v30
	v_add_f32_e32 v31, 1.0, v31
	s_nop 0
	v_mov_b32_e32 v30, v32
	v_sub_f32_e32 v18, v18, v30
	v_log_f32_e32 v31, v31
	v_mul_f32_e64 v32, |v20|, s33
	v_exp_f32_e32 v32, v32
	v_min_f32_e32 v20, 0, v20
	v_mul_f32_e32 v30, 0x3f317217, v31
	v_fma_f32 v30, v31, s2, -v30
	v_fmac_f32_e32 v30, 0x3377d1cf, v31
	v_fmac_f32_e32 v30, 0x3f317217, v31
	v_mul_f32_e32 v18, 0x3d800000, v18
	s_nop 0
	v_add_f32_e32 v31, 1.0, v32
	v_sub_f32_e32 v19, v19, v30
	v_mul_f32_e32 v19, 0x3d800000, v19
	v_log_f32_e32 v31, v31
	v_mul_f32_e64 v32, |v21|, s33
	v_exp_f32_e32 v32, v32
	v_min_f32_e32 v21, 0, v21
	v_mul_f32_e32 v30, 0x3f317217, v31
	v_fma_f32 v30, v31, s2, -v30
	v_fmac_f32_e32 v30, 0x3377d1cf, v31
	v_fmac_f32_e32 v30, 0x3f317217, v31
	s_nop 1
	v_add_f32_e32 v31, 1.0, v32
	v_sub_f32_e32 v20, v20, v30
	v_mul_f32_e32 v20, 0x3d800000, v20
	v_log_f32_e32 v31, v31
	v_mad_i32_i24 v32, v70, 48, v52
	v_or_b32_e32 v52, 35, v61
	v_mul_f32_e32 v30, 0x3f317217, v31
	v_fma_f32 v30, v31, s2, -v30
	v_fmac_f32_e32 v30, 0x3377d1cf, v31
	v_fmac_f32_e32 v30, 0x3f317217, v31
	s_nop 1
	v_sub_f32_e32 v21, v21, v30
	v_mul_f32_e32 v21, 0x3d800000, v21
	v_cvt_pk_bf16_f32 v30, v18, v19
	v_cvt_pk_bf16_f32 v31, v20, v21
	s_waitcnt vmcnt(3)
	v_mfma_f32_16x16x32_bf16 v[18:21], v[22:25], v[34:37], 0
	v_mul_lo_u32 v23, v32, s55
	v_add_u32_e32 v23, 0, v23
	v_lshlrev_b32_e32 v24, 5, v75
	v_add3_u32 v23, v23, v24, v61
	ds_write_b64 v23, v[30:31]
	s_waitcnt vmcnt(2)
	s_nop 1
	v_add_f32_e32 v18, v79, v18
	v_mul_f32_e64 v22, |v18|, s33
	v_exp_f32_e32 v22, v22
	v_add_f32_e32 v19, v79, v19
	v_mul_f32_e64 v24, |v19|, s33
	v_exp_f32_e32 v24, v24
	v_add_f32_e32 v22, 1.0, v22
	v_min_f32_e32 v18, 0, v18
	v_add_f32_e32 v20, v79, v20
	v_log_f32_e32 v22, v22
	v_min_f32_e32 v19, 0, v19
	v_add_f32_e32 v21, v79, v21
	v_or_b32_e32 v32, 1, v61
	v_mul_f32_e32 v23, 0x3f317217, v22
	v_fma_f32 v23, v22, s2, -v23
	v_fmac_f32_e32 v23, 0x3377d1cf, v22
	v_fmac_f32_e32 v23, 0x3f317217, v22
	v_or_b32_e32 v34, 3, v61
	v_or_b32_e32 v35, 4, v61
	v_mov_b32_e32 v22, v23
	v_add_f32_e32 v23, 1.0, v24
	v_sub_f32_e32 v18, v18, v22
	v_mul_f32_e32 v18, 0x3d800000, v18
	v_log_f32_e32 v23, v23
	v_mul_f32_e64 v24, |v20|, s33
	v_exp_f32_e32 v24, v24
	v_min_f32_e32 v20, 0, v20
	v_mul_f32_e32 v22, 0x3f317217, v23
	v_fma_f32 v22, v23, s2, -v22
	v_fmac_f32_e32 v22, 0x3377d1cf, v23
	v_fmac_f32_e32 v22, 0x3f317217, v23
	v_or_b32_e32 v36, 5, v61
	v_or_b32_e32 v37, 6, v61
	v_add_f32_e32 v23, 1.0, v24
	v_sub_f32_e32 v19, v19, v22
	v_mul_f32_e32 v19, 0x3d800000, v19
	v_log_f32_e32 v23, v23
	v_mul_f32_e64 v24, |v21|, s33
	v_exp_f32_e32 v24, v24
	v_min_f32_e32 v21, 0, v21
	v_mul_f32_e32 v22, 0x3f317217, v23
	v_fma_f32 v22, v23, s2, -v22
	v_fmac_f32_e32 v22, 0x3377d1cf, v23
	v_fmac_f32_e32 v22, 0x3f317217, v23
	s_nop 1
	v_add_f32_e32 v23, 1.0, v24
	v_sub_f32_e32 v20, v20, v22
	v_mul_f32_e32 v20, 0x3d800000, v20
	v_log_f32_e32 v23, v23
	v_mad_i32_i24 v24, v66, 48, v54
	v_mul_lo_u32 v24, v24, s55
	v_add_u32_e32 v24, 0, v24
	v_mul_f32_e32 v22, 0x3f317217, v23
	v_fma_f32 v22, v23, s2, -v22
	v_fmac_f32_e32 v22, 0x3377d1cf, v23
	v_fmac_f32_e32 v22, 0x3f317217, v23
	s_nop 1
	v_sub_f32_e32 v21, v21, v22
	v_mul_f32_e32 v21, 0x3d800000, v21
	v_cvt_pk_bf16_f32 v22, v18, v19
	v_cvt_pk_bf16_f32 v23, v20, v21
	s_waitcnt vmcnt(1)
; #define LAS __attribute__((address_space(3)))
; __device__ __forceinline__ unsigned pk_bf16(float lo, float hi) { unsigned r; asm volatile("v_cvt_pk_bf16_f32 %0, %1, %2" : "=v"(r) : "v"(lo), "v"(hi)); return r; }
; __device__ __forceinline__ f32x4 mfma16(bf16x8 a, bf16x8 b, f32x4 c) { return __builtin_amdgcn_mfma_f32_16x16x32_bf16(a, b, c, 0, 0, 0); }
; __device__ __forceinline__ void gla_prep(const PrepRegs& R, LAS unsigned char* lds, int wave, int fr, int fq) {
;     ...
;     for (int q = 0; q < 3; ++q) { const int tile = wave * 3 + q, mi = tile / 6, ni = tile % 6, dir = ni / 3, c = (ni % 3) * 16 + fr;
;         const f32x4 acc = mfma16(as_bf8(R.ga[q]), as_bf8(R.bw[q]), (f32x4){0.f, 0.f, 0.f, 0.f});
;         float g[4];
; #pragma unroll
;         for (int i = 0; i < 4; ++i) { const float sv = acc[i] + R.bias[q]; g[i] = (fminf(sv, 0.f) - __logf(1.f + __expf(-fabsf(sv)))) * (1.0f / 16.0f); }
;         u32x2 w2; w2.x = pk_bf16(g[0], g[1]); w2.y = pk_bf16(g[2], g[3]);
;         *(LAS u32x2*)(lds + GL_GT + (dir * 48 + c) * 144 + (mi * 16 + fq * 4) * 2) = w2; }
;     __syncthreads();
; #pragma unroll
;     for (int q = 0; q < 3; ++q) { const int tile = wave * 3 + q, mi = tile / 6, ni = tile % 6, dir = ni / 3;
;         f32x4 acc = (f32x4){0.f, 0.f, 0.f, 0.f};
; #pragma unroll
;         for (int kk = 0; kk < 2; ++kk) { const int t = mi * 16 + fr; bf16x8 tri;
; #pragma unroll
;             for (int e = 0; e < 8; ++e) { const int sidx = kk * 32 + fq * 8 + e; tri[e] = (dir ? (sidx >= t) : (sidx <= t)) ? (short)0x3F80 : (short)0; }
	v_mfma_f32_16x16x32_bf16 v[18:21], v[26:29], v[38:41], 0
	v_lshlrev_b32_e32 v26, 5, v76
	v_add3_u32 v24, v24, v26, v61
	ds_write_b64 v24, v[22:23]
	v_or_b32_e32 v38, 7, v61
	v_or_b32_e32 v39, 32, v61
	s_waitcnt vmcnt(0)
	s_nop 1
	v_add_f32_e32 v18, v80, v18
	v_mul_f32_e64 v25, |v18|, s33
	v_exp_f32_e32 v25, v25
	v_add_f32_e32 v19, v80, v19
	v_mul_f32_e64 v23, |v19|, s33
	v_exp_f32_e32 v23, v23
	v_add_f32_e32 v25, 1.0, v25
	v_min_f32_e32 v18, 0, v18
	v_add_f32_e32 v23, 1.0, v23
	v_log_f32_e32 v25, v25
	v_add_f32_e32 v20, v80, v20
	v_mul_f32_e32 v22, 0x3f317217, v25
	v_fma_f32 v22, v25, s2, -v22
	v_fmac_f32_e32 v22, 0x3377d1cf, v25
	v_fmac_f32_e32 v22, 0x3f317217, v25
	v_min_f32_e32 v19, 0, v19
	v_add_f32_e32 v21, v80, v21
	v_log_f32_e32 v23, v23
	v_sub_f32_e32 v18, v18, v22
	v_mul_f32_e64 v24, |v20|, s33
	v_exp_f32_e32 v24, v24
	v_mul_f32_e32 v22, 0x3f317217, v23
	v_fma_f32 v22, v23, s2, -v22
	v_fmac_f32_e32 v22, 0x3377d1cf, v23
	v_fmac_f32_e32 v22, 0x3f317217, v23
	v_min_f32_e32 v20, 0, v20
	v_mul_f32_e32 v18, 0x3d800000, v18
	v_add_f32_e32 v23, 1.0, v24
	v_sub_f32_e32 v19, v19, v22
	v_mul_f32_e32 v19, 0x3d800000, v19
	v_log_f32_e32 v23, v23
	v_mul_f32_e64 v24, |v21|, s33
	v_exp_f32_e32 v24, v24
	v_min_f32_e32 v21, 0, v21
	v_mul_f32_e32 v22, 0x3f317217, v23
	v_fma_f32 v22, v23, s2, -v22
	v_fmac_f32_e32 v22, 0x3377d1cf, v23
	v_fmac_f32_e32 v22, 0x3f317217, v23
	v_cvt_pk_bf16_f32 v18, v18, v19
	v_or_b32_e32 v40, 33, v61
	s_nop 0
	v_add_f32_e32 v23, 1.0, v24
	v_sub_f32_e32 v20, v20, v22
	v_mul_f32_e32 v20, 0x3d800000, v20
	v_log_f32_e32 v23, v23
	s_nop 0
	v_mul_f32_e32 v22, 0x3f317217, v23
	v_fma_f32 v22, v23, s2, -v22
	v_fmac_f32_e32 v22, 0x3377d1cf, v23
	v_fmac_f32_e32 v22, 0x3f317217, v23
	s_nop 1
	v_sub_f32_e32 v21, v21, v22
	v_mul_f32_e32 v21, 0x3d800000, v21
	v_cvt_pk_bf16_f32 v19, v20, v21
	v_mad_i32_i24 v20, v63, 48, v56
	v_mul_lo_u32 v20, v20, s55
	v_add_u32_e32 v20, 0, v20
	v_lshlrev_b32_e32 v21, 5, v77
	v_add3_u32 v20, v20, v21, v61
	ds_write_b64 v20, v[18:19]
	v_or_b32_e32 v19, v69, v43
	v_add_u32_e32 v18, 0, v0
	v_lshl_or_b32 v21, v74, 4, v43
	v_cmp_le_i32_e64 s[18:19], v61, v19
	v_add_u32_e32 v20, 2, v74
	v_mad_i32_i24 v28, v21, s55, v18
	v_cndmask_b32_e64 v21, 0, 1, s[18:19]
	v_cmp_ge_i32_e64 s[18:19], v61, v19
	s_waitcnt lgkmcnt(0)
	s_barrier
	s_lshr_b32 s101, s89, 7
	s_lshl_b32 s101, s101, 4
	v_add_u32_e32 v160, s101, v43
	v_sub_u32_e32 v160, v160, v61
	v_subrev_u32_e32 v161, 32, v160
	v_lshlrev_b32_e32 v160, 4, v160
	v_lshlrev_b32_e32 v161, 4, v161
	v_mov_b32_e32 v166, 0x3f803f80
	v_mov_b32_e32 v167, 0
	s_bitcmp1_b32 s89, 6
	s_cbranch_scc1 .Ltri_dir1_g1
	v_sub_u32_e32 v162, 16, v160
	v_med3_i32 v162, v162, 0, 32
	v_lshrrev_b64 v[164:165], v162, v[166:167]
	v_mov_b32_e32 v152, v164
	v_sub_u32_e32 v162, 48, v160
	v_med3_i32 v162, v162, 0, 32
	v_lshrrev_b64 v[164:165], v162, v[166:167]
	v_mov_b32_e32 v153, v164
	v_sub_u32_e32 v162, 0x50, v160
	v_med3_i32 v162, v162, 0, 32
	v_lshrrev_b64 v[164:165], v162, v[166:167]
	v_mov_b32_e32 v154, v164
	v_sub_u32_e32 v162, 0x70, v160
	v_med3_i32 v162, v162, 0, 32
	v_lshrrev_b64 v[164:165], v162, v[166:167]
	v_mov_b32_e32 v155, v164
	v_sub_u32_e32 v162, 16, v161
	v_med3_i32 v162, v162, 0, 32
	v_lshrrev_b64 v[164:165], v162, v[166:167]
	v_mov_b32_e32 v156, v164
	v_sub_u32_e32 v162, 48, v161
	v_med3_i32 v162, v162, 0, 32
	v_lshrrev_b64 v[164:165], v162, v[166:167]
	v_mov_b32_e32 v157, v164
	v_sub_u32_e32 v162, 0x50, v161
	v_med3_i32 v162, v162, 0, 32
	v_lshrrev_b64 v[164:165], v162, v[166:167]
	v_mov_b32_e32 v158, v164
	v_sub_u32_e32 v162, 0x70, v161
	v_med3_i32 v162, v162, 0, 32
	v_lshrrev_b64 v[164:165], v162, v[166:167]
	v_mov_b32_e32 v159, v164
	s_branch .Ltri_done_g1

; #define LAS __attribute__((address_space(3)))
; __device__ __forceinline__ unsigned pk_bf16(float lo, float hi) { unsigned r; asm volatile("v_cvt_pk_bf16_f32 %0, %1, %2" : "=v"(r) : "v"(lo), "v"(hi)); return r; }
; __device__ __forceinline__ f32x4 mfma16(bf16x8 a, bf16x8 b, f32x4 c) { return __builtin_amdgcn_mfma_f32_16x16x32_bf16(a, b, c, 0, 0, 0); }
; __device__ __forceinline__ void gla_prep(const PrepRegs& R, LAS unsigned char* lds, int wave, int fr, int fq) {
;     ...
;     for (int q = 0; q < 3; ++q) { const int tile = wave * 3 + q, mi = tile / 6, ni = tile % 6, dir = ni / 3, c = (ni % 3) * 16 + fr;
;         const f32x4 acc = mfma16(as_bf8(R.ga[q]), as_bf8(R.bw[q]), (f32x4){0.f, 0.f, 0.f, 0.f});
;         float g[4];
; #pragma unroll
;         for (int i = 0; i < 4; ++i) { const float sv = acc[i] + R.bias[q]; g[i] = (fminf(sv, 0.f) - __logf(1.f + __expf(-fabsf(sv)))) * (1.0f / 16.0f); }
;         u32x2 w2; w2.x = pk_bf16(g[0], g[1]); w2.y = pk_bf16(g[2], g[3]);
;         *(LAS u32x2*)(lds + GL_GT + (dir * 48 + c) * 144 + (mi * 16 + fq * 4) * 2) = w2; }
; __device__ __forceinline__ void gla_g3_item(int wv, const Params& p, int l, int b, int n, int h, LAS unsigned char* lds) {
;     ...
;     { const bf16_t* gp = Z + (size_t)(row0 + tf) * ZLD + ZC_GG + h * 96 + part * 12;
; #pragma unroll
;       for (int q4 = 0; q4 < 3; ++q4) ggw[q4] = *(const u32x2*)(gp + q4 * 4); }
.LBB0_991:
	s_or_b64 exec, exec, s[4:5]
	v_and_b32_e32 v59, 7, v83
	v_add_u32_e32 v58, s3, v63
	v_mov_b64_e32 v[60:61], s[36:37]
	v_mad_i64_i32 v[60:61], s[4:5], v58, s86, v[60:61]
	s_lshl_b32 s56, s34, 1
	v_mul_u32_u24_e32 v65, 12, v59
	v_lshl_add_u64 v[106:107], v[60:61], 0, s[56:57]
	v_lshlrev_b32_e32 v60, 1, v65
	v_mov_b32_e32 v61, v1
	v_lshl_add_u64 v[110:111], v[106:107], 0, v[60:61]
	s_waitcnt vmcnt(1)
	v_cvt_pk_bf16_f32 v46, v113, v112
	v_cvt_pk_bf16_f32 v47, v115, v114
	v_cvt_pk_bf16_f32 v48, v117, v116
	v_cvt_pk_bf16_f32 v49, v119, v118
	v_and_b32_e32 v46, v140, v46
	v_and_b32_e32 v47, v140, v47
	v_and_b32_e32 v48, v140, v48
	v_and_b32_e32 v49, v140, v49
	v_cvt_pk_bf16_f32 v50, v121, v120
	v_cvt_pk_bf16_f32 v51, v123, v122
	v_cvt_pk_bf16_f32 v52, v125, v124
	v_cvt_pk_bf16_f32 v53, v127, v126
	v_and_b32_e32 v50, v141, v50
	v_and_b32_e32 v51, v141, v51
	v_and_b32_e32 v52, v141, v52
	v_and_b32_e32 v53, v141, v53
	v_cvt_pk_bf16_f32 v54, v133, v132
	v_cvt_pk_bf16_f32 v55, v135, v134
	v_cvt_pk_bf16_f32 v56, v137, v136
	v_cvt_pk_bf16_f32 v57, v139, v138
	v_and_b32_e32 v54, v142, v54
	v_and_b32_e32 v55, v142, v55
	v_and_b32_e32 v56, v142, v56
	v_and_b32_e32 v57, v142, v57
	v_mfma_f32_16x16x32_bf16 v[106:109], v[6:9], v[46:49], 0
	s_waitcnt vmcnt(3)
	v_mfma_f32_16x16x32_bf16 v[38:41], v[38:41], v[50:53], 0
	v_lshlrev_b32_e32 v52, 5, v100
	s_nop 4
	v_add_f32_e32 v48, v103, v106
	v_mul_f32_e64 v6, |v48|, s33
	v_exp_f32_e32 v49, v6
	v_add_f32_e32 v61, v103, v107
	v_mul_f32_e64 v106, |v61|, s33
	v_exp_f32_e32 v106, v106
	v_add_f32_e32 v49, 1.0, v49
	v_min_f32_e32 v48, 0, v48
	s_waitcnt vmcnt(2)
	v_add_f32_e32 v38, v104, v38
	v_log_f32_e32 v49, v49
	v_mul_f32_e64 v50, |v38|, s33
	v_exp_f32_e32 v50, v50
	global_load_dwordx2 v[46:47], v[110:111], off offset:2320
	global_load_dwordx4 v[6:9], v[110:111], off offset:2304
	v_mul_f32_e32 v59, 0x3f317217, v49
	v_fma_f32 v59, v49, s2, -v59
	v_fmac_f32_e32 v59, 0x3377d1cf, v49
	v_fmac_f32_e32 v59, 0x3f317217, v49
	v_add_f32_e32 v50, 1.0, v50
	s_nop 0
	v_mov_b32_e32 v49, v59
	v_add_f32_e32 v59, 1.0, v106
	v_sub_f32_e32 v48, v48, v49
	v_min_f32_e32 v49, 0, v61
	v_log_f32_e32 v59, v59
	v_add_f32_e32 v106, v103, v108
	v_mul_f32_e64 v107, |v106|, s33
	v_exp_f32_e32 v107, v107
	v_mul_f32_e32 v61, 0x3f317217, v59
	v_fma_f32 v61, v59, s2, -v61
	v_fmac_f32_e32 v61, 0x3377d1cf, v59
	v_fmac_f32_e32 v61, 0x3f317217, v59
	v_add_f32_e32 v103, v103, v109
	v_mul_f32_e32 v48, 0x3d800000, v48
	v_mov_b32_e32 v59, v61
	v_add_f32_e32 v61, 1.0, v107
	v_sub_f32_e32 v49, v49, v59
	v_min_f32_e32 v59, 0, v106
	v_log_f32_e32 v61, v61
	v_mul_f32_e64 v107, |v103|, s33
	v_exp_f32_e32 v107, v107
	v_mul_f32_e32 v49, 0x3d800000, v49
	v_mul_f32_e32 v106, 0x3f317217, v61
	v_fma_f32 v106, v61, s2, -v106
	v_fmac_f32_e32 v106, 0x3377d1cf, v61
	v_fmac_f32_e32 v106, 0x3f317217, v61
	s_barrier
; #define LAS __attribute__((address_space(3)))
; __device__ __forceinline__ unsigned pk_bf16(float lo, float hi) { unsigned r; asm volatile("v_cvt_pk_bf16_f32 %0, %1, %2" : "=v"(r) : "v"(lo), "v"(hi)); return r; }
; __device__ __forceinline__ f32x4 mfma16(bf16x8 a, bf16x8 b, f32x4 c) { return __builtin_amdgcn_mfma_f32_16x16x32_bf16(a, b, c, 0, 0, 0); }
; __device__ __forceinline__ void gla_prep(const PrepRegs& R, LAS unsigned char* lds, int wave, int fr, int fq) {
;     ...
;     for (int q = 0; q < 3; ++q) { const int tile = wave * 3 + q, mi = tile / 6, ni = tile % 6, dir = ni / 3, c = (ni % 3) * 16 + fr;
;         const f32x4 acc = mfma16(as_bf8(R.ga[q]), as_bf8(R.bw[q]), (f32x4){0.f, 0.f, 0.f, 0.f});
;         float g[4];
; #pragma unroll
;         for (int i = 0; i < 4; ++i) { const float sv = acc[i] + R.bias[q]; g[i] = (fminf(sv, 0.f) - __logf(1.f + __expf(-fabsf(sv)))) * (1.0f / 16.0f); }
;         u32x2 w2; w2.x = pk_bf16(g[0], g[1]); w2.y = pk_bf16(g[2], g[3]);
;         *(LAS u32x2*)(lds + GL_GT + (dir * 48 + c) * 144 + (mi * 16 + fq * 4) * 2) = w2; }
;     __syncthreads();
; #pragma unroll
;     for (int q = 0; q < 3; ++q) { const int tile = wave * 3 + q, mi = tile / 6, ni = tile % 6, dir = ni / 3;
;         f32x4 acc = (f32x4){0.f, 0.f, 0.f, 0.f};
; #pragma unroll
;         for (int kk = 0; kk < 2; ++kk) { const int t = mi * 16 + fr; bf16x8 tri;
; #pragma unroll
;             for (int e = 0; e < 8; ++e) { const int sidx = kk * 32 + fq * 8 + e; tri[e] = (dir ? (sidx >= t) : (sidx <= t)) ? (short)0x3F80 : (short)0; }
	s_nop 0
	v_mov_b32_e32 v61, v106
	v_add_f32_e32 v106, 1.0, v107
	v_sub_f32_e32 v59, v59, v61
	v_min_f32_e32 v61, 0, v103
	v_log_f32_e32 v106, v106
	v_mul_f32_e32 v59, 0x3d800000, v59
	v_cvt_pk_bf16_f32 v48, v48, v49
	v_add_f32_e32 v39, v104, v39
	v_mul_f32_e32 v103, 0x3f317217, v106
	v_fma_f32 v103, v106, s2, -v103
	v_fmac_f32_e32 v103, 0x3377d1cf, v106
	v_fmac_f32_e32 v103, 0x3f317217, v106
	v_min_f32_e32 v38, 0, v38
	v_add_f32_e32 v40, v104, v40
	v_sub_f32_e32 v61, v61, v103
	v_mul_f32_e32 v61, 0x3d800000, v61
	v_cvt_pk_bf16_f32 v49, v59, v61
	v_mad_i32_i24 v59, v94, 48, v74
	v_mul_lo_u32 v51, v59, s55
	v_add_u32_e32 v51, 0, v51
	v_log_f32_e32 v50, v50
	v_add3_u32 v51, v51, v52, v84
	ds_write_b64 v51, v[48:49]
	v_mul_f32_e64 v49, |v39|, s33
	v_exp_f32_e32 v49, v49
	v_mul_f32_e32 v48, 0x3f317217, v50
	v_fma_f32 v48, v50, s2, -v48
	v_fmac_f32_e32 v48, 0x3377d1cf, v50
	v_fmac_f32_e32 v48, 0x3f317217, v50
	v_add_f32_e32 v49, 1.0, v49
	v_min_f32_e32 v39, 0, v39
	v_sub_f32_e32 v38, v38, v48
	v_log_f32_e32 v49, v49
	v_mul_f32_e64 v50, |v40|, s33
	v_exp_f32_e32 v50, v50
	v_add_f32_e32 v41, v104, v41
	v_mul_f32_e32 v48, 0x3f317217, v49
	v_fma_f32 v48, v49, s2, -v48
	v_fmac_f32_e32 v48, 0x3377d1cf, v49
	v_fmac_f32_e32 v48, 0x3f317217, v49
	v_min_f32_e32 v40, 0, v40
	v_mul_f32_e32 v38, 0x3d800000, v38
	v_add_f32_e32 v49, 1.0, v50
	v_sub_f32_e32 v39, v39, v48
	v_mul_f32_e32 v39, 0x3d800000, v39
	v_log_f32_e32 v49, v49
	v_mul_f32_e64 v50, |v41|, s33
	v_exp_f32_e32 v50, v50
	v_min_f32_e32 v41, 0, v41
	v_mul_f32_e32 v48, 0x3f317217, v49
	v_fma_f32 v48, v49, s2, -v48
	v_fmac_f32_e32 v48, 0x3377d1cf, v49
	v_fmac_f32_e32 v48, 0x3f317217, v49
	v_or_b32_e32 v59, 3, v84
	v_or_b32_e32 v61, 4, v84
	v_add_f32_e32 v49, 1.0, v50
	v_sub_f32_e32 v40, v40, v48
	v_mul_f32_e32 v40, 0x3d800000, v40
	v_log_f32_e32 v49, v49
	v_mad_i32_i24 v50, v89, 48, v76
	v_or_b32_e32 v74, 5, v84
	v_or_b32_e32 v76, 6, v84
	v_mul_f32_e32 v48, 0x3f317217, v49
	v_fma_f32 v48, v49, s2, -v48
	v_fmac_f32_e32 v48, 0x3377d1cf, v49
	v_fmac_f32_e32 v48, 0x3f317217, v49
	v_or_b32_e32 v100, 34, v84
	v_or_b32_e32 v103, 36, v84
	v_sub_f32_e32 v41, v41, v48
	v_mul_f32_e32 v41, 0x3d800000, v41
	v_cvt_pk_bf16_f32 v48, v38, v39
	v_cvt_pk_bf16_f32 v49, v40, v41
	s_waitcnt vmcnt(3)
	v_mfma_f32_16x16x32_bf16 v[38:41], v[42:45], v[54:57], 0
	v_mul_lo_u32 v43, v50, s55
	v_add_u32_e32 v43, 0, v43
	v_lshlrev_b32_e32 v44, 5, v101
	v_add3_u32 v43, v43, v44, v84
	ds_write_b64 v43, v[48:49]
	s_waitcnt vmcnt(2)
	s_nop 1
	v_add_f32_e32 v38, v105, v38
	v_mul_f32_e64 v42, |v38|, s33
	v_exp_f32_e32 v42, v42
	v_add_f32_e32 v39, v105, v39
	v_mul_f32_e64 v44, |v39|, s33
	v_exp_f32_e32 v44, v44
	v_add_f32_e32 v42, 1.0, v42
	v_min_f32_e32 v38, 0, v38
	v_add_f32_e32 v40, v105, v40
	v_log_f32_e32 v42, v42
	v_min_f32_e32 v39, 0, v39
	v_add_f32_e32 v41, v105, v41
	v_or_b32_e32 v56, 1, v84
	v_mul_f32_e32 v43, 0x3f317217, v42
	v_fma_f32 v43, v42, s2, -v43
	v_fmac_f32_e32 v43, 0x3377d1cf, v42
	v_fmac_f32_e32 v43, 0x3f317217, v42
	v_or_b32_e32 v57, 2, v84
	v_or_b32_e32 v101, 35, v84
	v_mov_b32_e32 v42, v43
	v_add_f32_e32 v43, 1.0, v44
	v_sub_f32_e32 v38, v38, v42
	v_mul_f32_e32 v38, 0x3d800000, v38
	v_log_f32_e32 v43, v43
	v_mul_f32_e64 v44, |v40|, s33
	v_exp_f32_e32 v44, v44
	v_min_f32_e32 v40, 0, v40
	v_mul_f32_e32 v42, 0x3f317217, v43
	v_fma_f32 v42, v43, s2, -v42
	v_fmac_f32_e32 v42, 0x3377d1cf, v43
	v_fmac_f32_e32 v42, 0x3f317217, v43
	v_or_b32_e32 v104, 37, v84
	v_or_b32_e32 v106, 38, v84
	v_add_f32_e32 v43, 1.0, v44
	v_sub_f32_e32 v39, v39, v42
	v_mul_f32_e32 v39, 0x3d800000, v39
	v_log_f32_e32 v43, v43
	v_mul_f32_e64 v44, |v41|, s33
	v_exp_f32_e32 v44, v44
	v_min_f32_e32 v41, 0, v41
	v_mul_f32_e32 v42, 0x3f317217, v43
	v_fma_f32 v42, v43, s2, -v42
	v_fmac_f32_e32 v42, 0x3377d1cf, v43
	v_fmac_f32_e32 v42, 0x3f317217, v43
	v_cvt_pk_bf16_f32 v38, v38, v39
	s_nop 1
	v_add_f32_e32 v43, 1.0, v44
	v_sub_f32_e32 v40, v40, v42
	v_mul_f32_e32 v40, 0x3d800000, v40
	v_log_f32_e32 v43, v43
	s_nop 0
	v_mul_f32_e32 v42, 0x3f317217, v43
	v_fma_f32 v42, v43, s2, -v42
	v_fmac_f32_e32 v42, 0x3377d1cf, v43
	v_fmac_f32_e32 v42, 0x3f317217, v43
	s_nop 1
	v_sub_f32_e32 v41, v41, v42
	v_mul_f32_e32 v41, 0x3d800000, v41
	v_cvt_pk_bf16_f32 v39, v40, v41
	v_mad_i32_i24 v40, v77, 48, v78
	v_mul_lo_u32 v40, v40, s55
	v_add_u32_e32 v40, 0, v40
	v_lshlrev_b32_e32 v41, 5, v102
	v_add3_u32 v40, v40, v41, v84
	ds_write_b64 v40, v[38:39]
	v_or_b32_e32 v39, v93, v81
	v_add_u32_e32 v38, 0, v0
	v_lshl_or_b32 v41, v99, 4, v81
	v_cmp_le_i32_e64 s[24:25], v84, v39
	v_add_u32_e32 v40, 2, v99
	v_mad_i32_i24 v44, v41, s55, v38
	v_cndmask_b32_e64 v41, 0, 1, s[24:25]
	v_cmp_ge_i32_e64 s[24:25], v84, v39
	v_or_b32_e32 v78, 7, v84
	s_waitcnt lgkmcnt(0)
	v_cndmask_b32_e64 v42, 0, 1, s[24:25]
	v_cmp_gt_u32_e64 s[24:25], 5, v40
	s_barrier
	s_lshr_b32 s101, s89, 7
	s_lshl_b32 s101, s101, 4
	v_add_u32_e32 v160, s101, v81
	v_sub_u32_e32 v160, v160, v84
	v_subrev_u32_e32 v161, 32, v160
	v_lshlrev_b32_e32 v160, 4, v160
	v_lshlrev_b32_e32 v161, 4, v161
	v_mov_b32_e32 v166, 0x3f803f80
	v_mov_b32_e32 v167, 0
	s_bitcmp1_b32 s89, 6
	s_cbranch_scc1 .Ltri_dir1_g3
	v_sub_u32_e32 v162, 16, v160
	v_med3_i32 v162, v162, 0, 32
	v_lshrrev_b64 v[164:165], v162, v[166:167]
	v_mov_b32_e32 v152, v164
	v_sub_u32_e32 v162, 48, v160
	v_med3_i32 v162, v162, 0, 32
	v_lshrrev_b64 v[164:165], v162, v[166:167]
	v_mov_b32_e32 v153, v164
	v_sub_u32_e32 v162, 0x50, v160
	v_med3_i32 v162, v162, 0, 32
	v_lshrrev_b64 v[164:165], v162, v[166:167]
	v_mov_b32_e32 v154, v164
	v_sub_u32_e32 v162, 0x70, v160
	v_med3_i32 v162, v162, 0, 32
	v_lshrrev_b64 v[164:165], v162, v[166:167]
	v_mov_b32_e32 v155, v164
	v_sub_u32_e32 v162, 16, v161
	v_med3_i32 v162, v162, 0, 32
	v_lshrrev_b64 v[164:165], v162, v[166:167]
	v_mov_b32_e32 v156, v164
	v_sub_u32_e32 v162, 48, v161
	v_med3_i32 v162, v162, 0, 32
	v_lshrrev_b64 v[164:165], v162, v[166:167]
	v_mov_b32_e32 v157, v164
	v_sub_u32_e32 v162, 0x50, v161
	v_med3_i32 v162, v162, 0, 32
	v_lshrrev_b64 v[164:165], v162, v[166:167]
	v_mov_b32_e32 v158, v164
	v_sub_u32_e32 v162, 0x70, v161
	v_med3_i32 v162, v162, 0, 32
	v_lshrrev_b64 v[164:165], v162, v[166:167]
	v_mov_b32_e32 v159, v164
	s_branch .Ltri_done_g3
